# weight-copy redistribution: 256 w_glu copy items moved from P5's pole path to P2's single-item waves, stacked on v78
# baseline (speedup 1.0000x reference)
.LBB0_434:
	s_and_b64 s[0:1], s[16:17], exec
	s_cselect_b32 s1, s18, 0
	s_cmp_lt_i32 s56, s1
	v_readlane_b32 s54, v255, 5
	s_cselect_b64 s[2:3], -1, 0
	s_cmp_le_i32 s54, s1
	s_cselect_b64 s[4:5], -1, 0
	s_or_b64 s[2:3], s[2:3], s[4:5]
	s_and_b64 vcc, exec, s[2:3]
	v_readlane_b32 s97, v255, 4
	v_readlane_b32 s33, v255, 10
	s_cbranch_vccnz .LBB0_641
	s_sub_i32 s0, s54, s1
	s_cmp_gt_i32 s0, 64
	s_movk_i32 s2, 0x1880
	s_cselect_b32 s28, s2, 0x1a80
	s_sub_i32 s1, s56, s1
	s_lshl_b32 s1, s1, 3
	v_readlane_b32 s2, v254, 61
	s_add_i32 s1, s2, s1
	s_add_i32 s29, s1, 0x1080
	s_cmp_ge_u32 s29, s28
	s_cbranch_scc1 .LBB0_640
	v_readlane_b32 s1, v254, 61
	s_mulk_i32 s1, 0x4200
	v_lshrrev_b32_e32 v110, 3, v186
	s_waitcnt lgkmcnt(0)
	v_and_b32_e32 v3, 56, v187
	s_add_i32 s1, s1, 0
	v_lshrrev_b32_e32 v66, 4, v186
	v_mul_u32_u24_e32 v4, 0x104, v3
	v_lshlrev_b32_e32 v68, 1, v3
	v_lshlrev_b32_e32 v3, 2, v110
	s_movk_i32 s2, 0x104
	v_add3_u32 v111, s1, v4, v3
	v_or_b32_e32 v3, 4, v66
	v_mov_b32_e32 v4, 0x410
	v_mad_u32_u24 v120, v3, s2, v4
	v_mov_b32_e32 v4, 0x820
	v_readlane_b32 s4, v255, 23
	v_mad_u32_u24 v121, v3, s2, v4
	v_mov_b32_e32 v4, 0xc30
	v_mov_b32_e32 v69, 0
	v_readlane_b32 s5, v255, 24
	v_mad_u32_u24 v122, v3, s2, v4
	v_mov_b32_e32 v4, 0x1040
	v_lshl_add_u64 v[70:71], s[4:5], 0, v[68:69]
	v_readlane_b32 s4, v255, 21
	v_mad_u32_u24 v123, v3, s2, v4
	v_mov_b32_e32 v4, 0x1450
	v_readlane_b32 s5, v255, 22
	v_mad_u32_u24 v124, v3, s2, v4
	v_mov_b32_e32 v4, 0x1860
	v_lshl_add_u64 v[72:73], s[4:5], 0, v[68:69]
	v_readlane_b32 s4, v255, 19
	v_mad_u32_u24 v125, v3, s2, v4
	v_mov_b32_e32 v4, 0x1c70
	v_readlane_b32 s5, v255, 20
	v_mad_u32_u24 v126, v3, s2, v4
	v_mov_b32_e32 v4, 0x2080
	v_lshlrev_b32_e32 v2, 4, v1
	v_lshl_add_u64 v[74:75], s[4:5], 0, v[68:69]
	v_mad_u32_u24 v127, v3, s2, v4
	v_mov_b32_e32 v4, 0x2490
	v_readlane_b32 s36, v254, 45
	v_readlane_b32 s4, v254, 29
	v_add_u32_e32 v108, s1, v2
	v_mad_u32_u24 v128, v3, s2, v4
	v_mov_b32_e32 v4, 0x28a0
	v_readlane_b32 s37, v254, 46
	v_readlane_b32 s38, v254, 47
	v_readlane_b32 s39, v254, 48
	v_readlane_b32 s40, v254, 49
	v_readlane_b32 s41, v254, 50
	v_readlane_b32 s42, v254, 51
	v_readlane_b32 s43, v254, 52
	v_readlane_b32 s44, v254, 53
	v_readlane_b32 s45, v254, 54
	v_readlane_b32 s12, v254, 37
	v_readlane_b32 s13, v254, 38
	v_mad_u32_u24 v109, v66, s2, v108
	v_mad_u32_u24 v129, v3, s2, v4
	v_readlane_b32 s2, v255, 17
	v_readlane_b32 s5, v254, 30
	v_readlane_b32 s6, v254, 31
	v_readlane_b32 s7, v254, 32
	v_readlane_b32 s8, v254, 33
	v_readlane_b32 s9, v254, 34
	v_readlane_b32 s10, v254, 35
	v_readlane_b32 s11, v254, 36
	s_mov_b64 s[44:45], s[12:13]
	v_readlane_b32 s3, v255, 18
	s_mov_b64 s[42:43], s[10:11]
	s_mov_b64 s[40:41], s[8:9]
	s_mov_b64 s[38:39], s[6:7]
	s_mov_b64 s[36:37], s[4:5]
	v_readlane_b32 s4, v254, 0
	v_mul_u32_u24_e32 v119, 0x104, v3
	v_lshl_add_u64 v[76:77], s[2:3], 0, v[68:69]
	v_readlane_b32 s2, v255, 13
	v_mov_b32_e32 v3, v69
	v_readlane_b32 s14, v254, 39
	v_readlane_b32 s15, v254, 40
	v_readlane_b32 s16, v254, 41
	v_readlane_b32 s17, v254, 42
	v_readlane_b32 s18, v254, 43
	v_readlane_b32 s19, v254, 44
	v_readlane_b32 s5, v254, 1
	v_readlane_b32 s6, v254, 2
	v_readlane_b32 s7, v254, 3
	v_readlane_b32 s8, v254, 4
	v_readlane_b32 s9, v254, 5
	v_readlane_b32 s10, v254, 6
	v_readlane_b32 s11, v254, 7
	v_readlane_b32 s3, v255, 14
	v_lshl_add_u64 v[94:95], s[8:9], 0, v[2:3]
	v_lshl_add_u64 v[96:97], s[6:7], 0, v[2:3]
	v_lshl_add_u64 v[98:99], s[4:5], 0, v[2:3]
	v_readlane_b32 s4, v254, 10
	s_lshl_b32 s30, s0, 3
	v_lshl_add_u64 v[78:79], s[2:3], 0, v[68:69]
	v_readlane_b32 s2, v255, 15
	v_readlane_b32 s5, v254, 11
	v_readlane_b32 s6, v254, 12
	v_readlane_b32 s7, v254, 13
	v_readlane_b32 s8, v254, 14
	v_readlane_b32 s9, v254, 15
	v_readlane_b32 s10, v254, 16
	v_readlane_b32 s11, v254, 17
	v_readlane_b32 s12, v254, 18
	v_readlane_b32 s13, v254, 19
	v_readlane_b32 s14, v254, 20
	v_readlane_b32 s15, v254, 21
	v_readlane_b32 s3, v255, 16
	v_readlane_b32 s50, v254, 59
	v_readlane_b32 s51, v254, 60
	v_readlane_b32 s16, v254, 22
	v_readlane_b32 s17, v254, 23
	v_readlane_b32 s18, v254, 24
	v_readlane_b32 s19, v254, 25
	s_mov_b64 s[4:5], s[8:9]
	s_cmp_lg_u64 s[38:39], 0
	v_lshl_add_u64 v[80:81], s[2:3], 0, v[68:69]
	v_readlane_b32 s2, v255, 2
	s_mov_b64 s[6:7], s[10:11]
	s_mov_b64 s[8:9], s[12:13]
	s_mov_b64 s[10:11], s[14:15]
	s_cselect_b64 s[4:5], -1, 0
	s_cmp_lg_u64 s[50:51], 0
	v_readlane_b32 s3, v255, 3
	v_readlane_b32 s46, v254, 55
	v_readlane_b32 s47, v254, 56
	v_readlane_b32 s48, v254, 57
	v_readlane_b32 s49, v254, 58
	s_mov_b64 s[12:13], s[16:17]
	s_mov_b64 s[14:15], s[18:19]
	s_cselect_b64 s[6:7], -1, 0
	s_cmp_lg_u64 s[10:11], 0
	v_or_b32_e32 v112, 8, v110
	v_or_b32_e32 v113, 16, v110
	v_or_b32_e32 v114, 24, v110
	v_or_b32_e32 v115, 32, v110
	v_or_b32_e32 v116, 40, v110
	v_or_b32_e32 v117, 48, v110
	v_or_b32_e32 v118, 56, v110
	v_lshl_add_u64 v[82:83], s[2:3], 0, v[68:69]
	v_lshl_add_u64 v[84:85], s[68:69], 0, v[68:69]
	v_lshl_add_u64 v[86:87], s[48:49], 0, v[2:3]
	v_lshl_add_u64 v[88:89], s[46:47], 0, v[2:3]
	v_lshl_add_u64 v[90:91], s[44:45], 0, v[2:3]
	v_lshl_add_u64 v[92:93], s[40:41], 0, v[2:3]
	v_lshl_add_u64 v[100:101], s[36:37], 0, v[2:3]
	v_lshl_add_u64 v[102:103], s[14:15], 0, v[2:3]
	v_lshl_add_u64 v[104:105], s[12:13], 0, v[2:3]
	s_cselect_b64 s[8:9], -1, 0
	v_mov_b32_e32 v67, v69
	s_lshl_b32 s31, s29, 6
	s_lshl_b32 s34, s0, 9
	s_lshl_b32 s35, s29, 7
	s_lshl_b32 s38, s0, 10
	s_lshl_b32 s39, s29, 2
	s_lshl_b32 s40, s0, 5
	s_lshl_b32 s41, s29, 1
	s_lshl_b32 s44, s0, 4
	s_movk_i32 s45, 0x2c00
	s_mov_b32 s46, 0xb000
	s_mov_b32 s47, 0x16000
	s_mov_b32 s48, 0x21000
	s_mov_b32 s49, 0x2c000
	s_mov_b32 s50, 0x37000
	s_mov_b32 s51, 0x42000
	s_mov_b32 s62, 0x4d000
	s_mov_b32 s63, 0x58000
	s_mov_b32 s64, 0x63000
	s_mov_b32 s65, 0x6e000
	s_mov_b32 s66, 0x79000
	s_mov_b32 s67, 0x84000
	s_mov_b32 s13, 0
	s_branch .LBB0_440

.LBB0_1028:
	s_cmpk_lt_i32 s2, 0x41
	s_cselect_b64 s[0:1], -1, 0
	s_add_i32 s25, s25, 64
	s_cmp_lt_i32 s56, s25
	s_cselect_b64 s[6:7], -1, 0
	s_or_b64 s[0:1], s[0:1], s[6:7]
	s_andn2_b64 vcc, exec, s[0:1]
	s_cbranch_vccz .LBB0_1235
	s_lshl_b32 s0, s3, 3
	v_readlane_b32 s1, v254, 61
	s_add_i32 s0, s1, s0
	s_addk_i32 s0, 0xfe00
	s_cmpk_gt_i32 s0, 0x1ff
	s_waitcnt vmcnt(0) lgkmcnt(0)
	s_barrier
	s_cbranch_scc1 .LBB0_1234
	s_add_i32 s26, s0, 0x1880
	v_readlane_b32 s0, v254, 61
	s_mulk_i32 s0, 0x4200
	v_lshrrev_b32_e32 v110, 3, v186
	v_and_b32_e32 v3, 56, v187
	s_add_i32 s0, s0, 0
	v_lshrrev_b32_e32 v66, 4, v186
	v_mul_u32_u24_e32 v4, 0x104, v3
	v_lshlrev_b32_e32 v68, 1, v3
	v_lshlrev_b32_e32 v3, 2, v110
	s_movk_i32 s1, 0x104
	v_add3_u32 v111, s0, v4, v3
	v_or_b32_e32 v3, 4, v66
	v_mov_b32_e32 v4, 0x410
	v_mad_u32_u24 v120, v3, s1, v4
	v_mov_b32_e32 v4, 0x820
	v_mad_u32_u24 v121, v3, s1, v4
	v_mov_b32_e32 v4, 0xc30
	v_mad_u32_u24 v122, v3, s1, v4
	v_mov_b32_e32 v4, 0x1040
	v_mad_u32_u24 v123, v3, s1, v4
	v_mov_b32_e32 v4, 0x1450
	v_mad_u32_u24 v124, v3, s1, v4
	v_mov_b32_e32 v4, 0x1860
	v_mad_u32_u24 v125, v3, s1, v4
	v_mov_b32_e32 v4, 0x1c70
	v_mad_u32_u24 v126, v3, s1, v4
	v_mov_b32_e32 v4, 0x2080
	v_lshlrev_b32_e32 v2, 4, v1
	v_mad_u32_u24 v127, v3, s1, v4
	v_mov_b32_e32 v4, 0x2490
	v_readlane_b32 s72, v254, 45
	v_add_u32_e32 v108, s0, v2
	v_mad_u32_u24 v128, v3, s1, v4
	v_mov_b32_e32 v4, 0x28a0
	v_readlane_b32 s84, v254, 57
	v_readlane_b32 s85, v254, 58
	v_mad_u32_u24 v109, v66, s1, v108
	v_mad_u32_u24 v129, v3, s1, v4
	v_readlane_b32 s0, v255, 17
	v_readlane_b32 s73, v254, 46
	v_readlane_b32 s74, v254, 47
	v_readlane_b32 s75, v254, 48
	v_readlane_b32 s76, v254, 49
	v_readlane_b32 s77, v254, 50
	v_readlane_b32 s78, v254, 51
	v_readlane_b32 s79, v254, 52
	v_readlane_b32 s80, v254, 53
	v_readlane_b32 s81, v254, 54
	v_readlane_b32 s82, v254, 55
	v_readlane_b32 s83, v254, 56
	v_readlane_b32 s86, v254, 59
	v_readlane_b32 s87, v254, 60
	s_mov_b64 s[16:17], s[84:85]
	v_mov_b32_e32 v69, 0
	v_readlane_b32 s1, v255, 18
	s_mov_b64 s[18:19], s[86:87]
	s_mov_b64 s[14:15], s[82:83]
	v_readlane_b32 s72, v254, 29
	v_readlane_b32 s6, v255, 23
	v_lshl_add_u64 v[76:77], s[0:1], 0, v[68:69]
	v_readlane_b32 s0, v255, 13
	v_readlane_b32 s73, v254, 30
	s_lshl_b32 s2, s2, 3
	v_readlane_b32 s7, v255, 24
	v_mul_u32_u24_e32 v119, 0x104, v3
	v_readlane_b32 s1, v255, 14
	v_mov_b32_e32 v3, v69
	v_readlane_b32 s74, v254, 31
	v_readlane_b32 s75, v254, 32
	v_readlane_b32 s76, v254, 33
	v_readlane_b32 s77, v254, 34
	v_readlane_b32 s78, v254, 35
	v_readlane_b32 s79, v254, 36
	v_readlane_b32 s80, v254, 37
	v_readlane_b32 s81, v254, 38
	v_readlane_b32 s82, v254, 39
	v_readlane_b32 s83, v254, 40
	v_readlane_b32 s84, v254, 41
	v_readlane_b32 s85, v254, 42
	v_readlane_b32 s86, v254, 43
	v_readlane_b32 s87, v254, 44
	s_mov_b64 s[36:37], s[72:73]
	s_addk_i32 s2, 0xfe00
	v_lshl_add_u64 v[70:71], s[6:7], 0, v[68:69]
	v_readlane_b32 s6, v255, 21
	v_lshl_add_u64 v[78:79], s[0:1], 0, v[68:69]
	v_readlane_b32 s0, v255, 15
	v_lshl_add_u64 v[88:89], s[14:15], 0, v[2:3]
	s_mov_b64 s[38:39], s[74:75]
	s_mov_b64 s[40:41], s[76:77]
	s_mov_b64 s[44:45], s[80:81]
	v_readlane_b32 s8, v254, 0
	v_readlane_b32 s72, v254, 10
	v_readlane_b32 s7, v255, 22
	v_readlane_b32 s1, v255, 16
	v_readlane_b32 s9, v254, 1
	v_readlane_b32 s12, v254, 4
	v_readlane_b32 s13, v254, 5
	v_readlane_b32 s14, v254, 6
	v_readlane_b32 s15, v254, 7
	v_readlane_b32 s84, v254, 22
	v_readlane_b32 s85, v254, 23
	s_cmp_lg_u64 s[38:39], 0
	v_lshl_add_u64 v[72:73], s[6:7], 0, v[68:69]
	v_readlane_b32 s6, v255, 19
	v_lshl_add_u64 v[80:81], s[0:1], 0, v[68:69]
	v_readlane_b32 s0, v255, 2
	v_lshl_add_u64 v[94:95], s[12:13], 0, v[2:3]
	v_lshl_add_u64 v[98:99], s[8:9], 0, v[2:3]
	v_readlane_b32 s82, v254, 20
	v_readlane_b32 s83, v254, 21
	v_readlane_b32 s86, v254, 24
	v_readlane_b32 s87, v254, 25
	s_mov_b64 s[12:13], s[84:85]
	s_cselect_b64 s[8:9], -1, 0
	s_cmp_lg_u64 s[18:19], 0
	v_readlane_b32 s7, v255, 20
	v_readlane_b32 s1, v255, 3
	v_readlane_b32 s10, v254, 2
	v_readlane_b32 s11, v254, 3
	s_mov_b64 s[14:15], s[86:87]
	v_lshl_add_u64 v[104:105], s[12:13], 0, v[2:3]
	s_cselect_b64 s[12:13], -1, 0
	s_cmp_lg_u64 s[82:83], 0
	v_or_b32_e32 v112, 8, v110
	v_or_b32_e32 v113, 16, v110
	v_or_b32_e32 v114, 24, v110
	v_or_b32_e32 v115, 32, v110
	v_or_b32_e32 v116, 40, v110
	v_or_b32_e32 v117, 48, v110
	v_or_b32_e32 v118, 56, v110
	v_lshl_add_u64 v[74:75], s[6:7], 0, v[68:69]
	v_lshl_add_u64 v[82:83], s[0:1], 0, v[68:69]
	v_lshl_add_u64 v[84:85], s[68:69], 0, v[68:69]
	v_lshl_add_u64 v[86:87], s[16:17], 0, v[2:3]
	v_lshl_add_u64 v[90:91], s[44:45], 0, v[2:3]
	v_lshl_add_u64 v[92:93], s[40:41], 0, v[2:3]
	v_lshl_add_u64 v[96:97], s[10:11], 0, v[2:3]
	v_lshl_add_u64 v[100:101], s[36:37], 0, v[2:3]
	v_lshl_add_u64 v[102:103], s[14:15], 0, v[2:3]
	s_cselect_b64 s[14:15], -1, 0
	v_mov_b32_e32 v67, v69
	s_lshl_b32 s27, s26, 6
	s_lshl_b32 s28, s2, 6
	s_lshl_b32 s29, s26, 7
	s_lshl_b32 s30, s2, 7
	s_lshl_b32 s31, s26, 2
	s_lshl_b32 s34, s2, 2
	s_lshl_b32 s35, s26, 1
	s_lshl_b32 s38, s2, 1
	s_movk_i32 s39, 0x6000
	s_movk_i32 s40, 0x2c00
	s_mov_b32 s41, 0xb000
	s_mov_b32 s44, 0x16000
	s_mov_b32 s45, 0x21000
	s_mov_b32 s46, 0x2c000
	s_mov_b32 s47, 0x37000
	s_mov_b32 s48, 0x42000
	s_mov_b32 s49, 0x4d000
	s_mov_b32 s50, 0x58000
	s_mov_b32 s51, 0x63000
	s_mov_b32 s56, 0x6e000
	s_mov_b32 s57, 0x79000
	s_mov_b32 s58, 0x84000
	s_mov_b32 s17, 0
	v_readlane_b32 s73, v254, 11
	v_readlane_b32 s74, v254, 12
	v_readlane_b32 s75, v254, 13
	v_readlane_b32 s76, v254, 14
	v_readlane_b32 s77, v254, 15
	v_readlane_b32 s78, v254, 16
	v_readlane_b32 s79, v254, 17
	v_readlane_b32 s80, v254, 18
	v_readlane_b32 s81, v254, 19
	s_branch .LBB0_1034
